# FoX hot loop: wave-0 log-forget scan via DPP prefix sum, row-max reductions via permlane16/32 swaps instead of LDS bpermute round trips
# speedup vs baseline: 1.1212x; 1.0155x over previous
.LBB0_1045:
	s_add_i32 s38, s36, 0x7f
	s_and_b32 s1, s38, 1
	s_lshl_b32 s0, s1, 4
	s_or_b32 s28, s0, 0xdb0c
	s_add_i32 s0, s0, 0xdb14
	v_mov_b32_e32 v76, s0
	ds_read2_b32 v[76:77], v76 offset1:1
	s_lshl_b32 s0, s37, 2
	v_mov_b32_e32 v78, s28
	v_mov_b32_e32 v79, s0
	ds_read_b32 v80, v79 offset:56064
	ds_read2_b32 v[78:79], v78 offset1:1
	s_waitcnt lgkmcnt(2)
	v_max_f32_e32 v77, v77, v77
	v_max_f32_e32 v76, v76, v76
	v_min_f32_e32 v76, v76, v77
	s_waitcnt lgkmcnt(1)
	v_add_f32_e32 v77, v0, v80
	s_waitcnt lgkmcnt(0)
	v_min3_f32 v76, v78, v79, v76
	v_cmp_lt_f32_e64 s[28:29], v77, v76
	s_and_b64 vcc, exec, s[28:29]
	s_cbranch_vccnz .LBB0_1063
	s_add_i32 s0, s37, 1
	s_cmp_lg_u32 s37, 2
	s_cselect_b32 s0, s0, 0
	s_cmp_ge_u32 s38, s58
	s_cbranch_scc1 .LBB0_1052
	s_mul_i32 s39, s0, 0x2400
	v_lshl_add_u32 v76, v164, 1, s39
	s_waitcnt vmcnt(3)
	ds_write_b128 v76, v[20:23]
	s_waitcnt vmcnt(2)
	ds_write_b128 v76, v[24:27] offset:27648
	s_waitcnt vmcnt(1)
	ds_write_b128 v76, v[28:31] offset:4608
	s_waitcnt vmcnt(0)
	ds_write_b128 v76, v[32:35] offset:32256
	s_and_saveexec_b64 s[30:31], s[12:13]
	s_cbranch_execz .LBB0_1051
	v_lshl_or_b32 v78, s0, 8, v176
	v_mov_b32_e32 v76, v191
	s_nop 1
	v_add_f32_dpp v76, v76, v76 row_shr:1 row_mask:0xf bank_mask:0xf
	s_nop 1
	v_add_f32_dpp v76, v76, v76 row_shr:2 row_mask:0xf bank_mask:0xf
	s_nop 1
	v_add_f32_dpp v76, v76, v76 row_shr:4 row_mask:0xf bank_mask:0xf
	s_nop 1
	v_add_f32_dpp v76, v76, v76 row_shr:8 row_mask:0xf bank_mask:0xf
	s_nop 1
	v_add_f32_dpp v76, v76, v76 row_bcast:15 row_mask:0xa bank_mask:0xf
	s_nop 1
	v_add_f32_dpp v76, v76, v76 row_bcast:31 row_mask:0xc bank_mask:0xf
	s_nop 1
	v_readlane_b32 s40, v76, 63
	s_nop 1
	v_sub_f32_e32 v77, s40, v76
	v_add_f32_e32 v77, v193, v77
	ds_write_b32 v78, v77 offset:55296
	v_mov_b32_e32 v76, v193
	v_add_f32_e32 v193, s40, v193
	s_and_saveexec_b64 s[34:35], s[26:27]
	s_mul_i32 s40, s0, 0xffffdc04
	s_add_i32 s39, s39, s40
	v_mov_b32_e32 v77, s39
	ds_write_b32 v77, v76 offset:56064
	s_or_b64 exec, exec, s[34:35]

.LBB0_1056:
	s_mul_i32 s30, s37, 0x2400
	v_add_u32_e32 v80, s30, v184
	ds_read_b128 v[76:79], v80
	ds_read_b128 v[92:95], v80 offset:64
	s_lshl_b32 s30, s37, 8
	v_lshl_or_b32 v123, v159, 2, s30
	s_waitcnt lgkmcnt(1)
	v_mfma_f32_16x16x32_bf16 v[96:99], v[76:79], v[4:7], 0
	v_mfma_f32_16x16x32_bf16 v[100:103], v[76:79], v[12:15], 0
	ds_read_b128 v[76:79], v80 offset:2304
	ds_read_b128 v[206:209], v80 offset:2368
	ds_read_b128 v[214:217], v80 offset:4608
	ds_read_b128 v[218:221], v80 offset:4672
	ds_read_b128 v[222:225], v80 offset:6912
	ds_read_b128 v[226:229], v80 offset:6976
	s_waitcnt lgkmcnt(5)
	v_mfma_f32_16x16x32_bf16 v[104:107], v[76:79], v[4:7], 0
	v_mfma_f32_16x16x32_bf16 v[210:213], v[76:79], v[12:15], 0
	s_waitcnt lgkmcnt(3)
	v_mfma_f32_16x16x32_bf16 v[76:79], v[214:217], v[4:7], 0
	v_mfma_f32_16x16x32_bf16 v[96:99], v[92:95], v[8:11], v[96:99]
	v_mfma_f32_16x16x32_bf16 v[104:107], v[206:209], v[8:11], v[104:107]
	s_waitcnt lgkmcnt(1)
	v_mfma_f32_16x16x32_bf16 v[108:111], v[222:225], v[4:7], 0
	v_mfma_f32_16x16x32_bf16 v[144:147], v[218:221], v[8:11], v[76:79]
	ds_read_b128 v[88:91], v123 offset:55296
	ds_read_b128 v[84:87], v123 offset:55360
	ds_read_b128 v[80:83], v123 offset:55424
	ds_read_b128 v[76:79], v123 offset:55488
	s_waitcnt lgkmcnt(3)
	v_pk_add_f32 v[152:153], v[96:97], v[88:89]
	s_waitcnt lgkmcnt(2)
	v_pk_add_f32 v[148:149], v[104:105], v[84:85]
	v_pk_add_f32 v[150:151], v[98:99], v[90:91]
	v_max3_f32 v104, v152, s94, v153
	v_mfma_f32_16x16x32_bf16 v[108:111], v[226:229], v[8:11], v[108:111]
	v_max3_f32 v104, v104, v150, v151
	s_waitcnt lgkmcnt(1)
	v_pk_add_f32 v[142:143], v[146:147], v[82:83]
	v_pk_add_f32 v[146:147], v[106:107], v[86:87]
	v_max3_f32 v104, v104, v148, v149
	v_pk_add_f32 v[144:145], v[144:145], v[80:81]
	v_max3_f32 v104, v104, v146, v147
	v_max3_f32 v104, v104, v144, v145
	s_waitcnt lgkmcnt(0)
	v_pk_add_f32 v[140:141], v[108:109], v[76:77]
	v_max3_f32 v104, v104, v142, v143
	v_pk_add_f32 v[110:111], v[110:111], v[78:79]
	v_max3_f32 v108, v104, v140, v141
	v_mfma_f32_16x16x32_bf16 v[104:107], v[92:95], v[16:19], v[100:103]
	v_max3_f32 v92, v108, v110, v111
	v_mov_b32_e32 v93, v92
	s_nop 1
	v_permlane16_swap_b32 v93, v92
	s_waitcnt lgkmcnt(0)
	v_max_f32_e32 v92, v92, v93
	v_mov_b32_e32 v93, v92
	s_nop 1
	v_permlane32_swap_b32 v93, v92
	v_mfma_f32_16x16x32_bf16 v[96:99], v[214:217], v[12:15], 0
	s_waitcnt lgkmcnt(0)
	v_max3_f32 v108, v2, v92, v93
	v_mfma_f32_16x16x32_bf16 v[214:217], v[222:225], v[12:15], 0
	v_cmp_neq_f32_e32 vcc, s94, v108
	v_mfma_f32_16x16x32_bf16 v[100:103], v[206:209], v[16:19], v[210:213]
	s_nop 0
	v_cndmask_b32_e32 v123, 0, v108, vcc
	v_cmp_gt_f32_e32 vcc, v108, v2
	v_mfma_f32_16x16x32_bf16 v[96:99], v[218:221], v[16:19], v[96:99]
	v_mfma_f32_16x16x32_bf16 v[92:95], v[226:229], v[16:19], v[214:217]
	s_cbranch_vccz .LBB0_1058
	v_sub_f32_e32 v2, v2, v123
	v_exp_f32_e32 v2, v2
	s_nop 0
	v_pk_mul_f32 v[74:75], v[74:75], v[2:3] op_sel_hi:[1,0]
	v_pk_mul_f32 v[72:73], v[72:73], v[2:3] op_sel_hi:[1,0]
	v_pk_mul_f32 v[70:71], v[70:71], v[2:3] op_sel_hi:[1,0]
	v_pk_mul_f32 v[68:69], v[68:69], v[2:3] op_sel_hi:[1,0]
	v_pk_mul_f32 v[66:67], v[66:67], v[2:3] op_sel_hi:[1,0]
	v_pk_mul_f32 v[64:65], v[64:65], v[2:3] op_sel_hi:[1,0]
	v_pk_mul_f32 v[58:59], v[58:59], v[2:3] op_sel_hi:[1,0]
	v_pk_mul_f32 v[56:57], v[56:57], v[2:3] op_sel_hi:[1,0]
	v_pk_mul_f32 v[62:63], v[62:63], v[2:3] op_sel_hi:[1,0]
	v_pk_mul_f32 v[60:61], v[60:61], v[2:3] op_sel_hi:[1,0]
.LBB0_1058:
	v_pk_add_f32 v[88:89], v[104:105], v[88:89]
	v_pk_add_f32 v[90:91], v[106:107], v[90:91]
	v_max3_f32 v2, v88, s94, v89
	v_pk_add_f32 v[84:85], v[100:101], v[84:85]
	v_max3_f32 v2, v2, v90, v91
	v_pk_add_f32 v[86:87], v[102:103], v[86:87]
	v_max3_f32 v2, v2, v84, v85
	v_pk_add_f32 v[80:81], v[96:97], v[80:81]
	v_max3_f32 v2, v2, v86, v87
	v_pk_add_f32 v[82:83], v[98:99], v[82:83]
	v_max3_f32 v2, v2, v80, v81
	v_pk_add_f32 v[76:77], v[92:93], v[76:77]
	v_max3_f32 v2, v2, v82, v83
	v_pk_add_f32 v[78:79], v[94:95], v[78:79]
	v_max3_f32 v2, v2, v76, v77
	v_max3_f32 v2, v2, v78, v79
	v_mov_b32_e32 v92, v2
	s_nop 1
	v_permlane16_swap_b32 v92, v2
	s_waitcnt lgkmcnt(0)
	v_max_f32_e32 v2, v2, v92
	v_mov_b32_e32 v92, v2
	s_nop 1
	v_permlane32_swap_b32 v92, v2
	s_waitcnt lgkmcnt(0)
	v_max3_f32 v109, v3, v2, v92
	v_cmp_neq_f32_e32 vcc, s94, v109
	s_nop 1
	v_cndmask_b32_e32 v2, 0, v109, vcc
	v_cmp_gt_f32_e32 vcc, v109, v3
	s_cbranch_vccz .LBB0_1060
	v_sub_f32_e32 v3, v3, v2
	v_exp_f32_e32 v92, v3
	s_nop 0
	v_pk_mul_f32 v[42:43], v[42:43], v[92:93] op_sel_hi:[1,0]
	v_pk_mul_f32 v[40:41], v[40:41], v[92:93] op_sel_hi:[1,0]
	v_pk_mul_f32 v[54:55], v[54:55], v[92:93] op_sel_hi:[1,0]
	v_pk_mul_f32 v[52:53], v[52:53], v[92:93] op_sel_hi:[1,0]
	v_pk_mul_f32 v[50:51], v[50:51], v[92:93] op_sel_hi:[1,0]
	v_pk_mul_f32 v[48:49], v[48:49], v[92:93] op_sel_hi:[1,0]
	v_pk_mul_f32 v[46:47], v[46:47], v[92:93] op_sel_hi:[1,0]
	v_pk_mul_f32 v[44:45], v[44:45], v[92:93] op_sel_hi:[1,0]
	v_pk_mul_f32 v[38:39], v[38:39], v[92:93] op_sel_hi:[1,0]
	v_pk_mul_f32 v[36:37], v[36:37], v[92:93] op_sel_hi:[1,0]
